# FoX pair loop: K/F/V LDS fragment reads hoisted ahead of their MFMAs (counted lgkmcnt)
# speedup vs baseline: 1.0206x; 1.0035x over previous
; #define LAS3 __attribute__((address_space(3)))
; __device__ __forceinline__ unsigned cvtpk(float lo, float hi) { f32x2_t v = {lo, hi}; bf16x2_t b = __builtin_convertvector(v, bf16x2_t); return __builtin_bit_cast(unsigned, b); }
; __device__ __forceinline__ s16x4 vtr(const LAS3 unsigned char* p) { return __builtin_bit_cast(s16x4, __builtin_amdgcn_ds_read_tr16_b64_v4i16((LAS3 v4i16_t*)p)); }
; __device__ __forceinline__ void fox_unit(int b, int hh, int qb, const bf16_t* Q, const bf16_t* __restrict__ K, const bf16_t* __restrict__ V, bf16_t* O, ...
;     ...
;             const LAS3 unsigned char* kp = kp0 + slot * SLOTB; const LAS3 unsigned char* fp = fp0 + slot * 1024;
;             asm volatile("" : "+v"(cinit));
;             f32x16 p0 = __builtin_amdgcn_mfma_f32_32x32x16_bf16(*(const LAS3 bf16x8*)(fp), qones, cinit, 0, 0, 0);
;             f32x16 p1 = __builtin_amdgcn_mfma_f32_32x32x16_bf16(*(const LAS3 bf16x8*)(fp + 512), qones, cinit, 0, 0, 0);
; #pragma unroll
;             for (int d0 = 0; d0 < 4; ++d0) {
;                 const bf16x8 k0 = *(const LAS3 bf16x8*)(kp + d0 * 2048), k1 = *(const LAS3 bf16x8*)(kp + d0 * 2048 + 512);
;                 p0 = __builtin_amdgcn_mfma_f32_32x32x16_bf16(k0, qr[d0], p0, 0, 0, 0);
;                 p1 = __builtin_amdgcn_mfma_f32_32x32x16_bf16(k1, qr[d0], p1, 0, 0, 0);
;             }
;             if (64 * jt + 63 > qw0) { const int kb_ = 64 * jt + 4 * hi - (qw0 + r32);
; #pragma unroll
;                 for (int r = 0; r < 16; ++r) { const int cr = (r & 3) + 8 * (r >> 2); if (kb_ + cr > 0) p0[r] = -INFINITY; if (kb_ + cr + 32 > 0) p1[r] = -INFINITY; } }
; #pragma unroll
;             for (int r = 0; r < 16; ++r) { p0[r] = __builtin_amdgcn_exp2f(p0[r]); p1[r] = __builtin_amdgcn_exp2f(p1[r]); }
;             u32x4 pw[4];
; #pragma unroll
;             for (int i = 0; i < 4; ++i) { pw[0][i] = cvtpk(p0[2 * i], p0[2 * i + 1]); pw[1][i] = cvtpk(p0[8 + 2 * i], p0[8 + 2 * i + 1]); pw[2][i] = cvtpk(p1[2 * i], p1[2 * i + 1]); pw[3][i] = cvtpk(p1[8 + 2 * i], p1[8 + 2 * i + 1]); }
;             const LAS3 unsigned char* vp = vp0 + slot * SLOTB;
; #pragma unroll
;             for (int ks = 0; ks < 4; ++ks) {
;                 const s16x4 l0 = vtr(vp + ks * 1024), h0 = vtr(vp + ks * 1024 + 512), l1 = vtr(vp + 4096 + ks * 1024), h1 = vtr(vp + 4096 + ks * 1024 + 512);
.LBB0_427:
	s_cmp_ge_i32 s3, s74
	s_cselect_b64 s[12:13], -1, 0
	s_or_b64 s[94:95], s[84:85], s[12:13]
	s_add_i32 s12, s96, s71
	s_add_i32 s7, s12, 0x1fc0
	s_cmp_le_u32 s7, s33
	s_cselect_b64 s[14:15], -1, 0
	s_and_b64 s[14:15], s[14:15], s[94:95]
	s_andn2_b64 vcc, exec, s[14:15]
	s_cbranch_vccnz .LBB0_431
	s_add_i32 s7, s6, -1
	s_and_b32 s7, s7, 3
	v_lshl_add_u32 v2, s7, 10, v166
	ds_read_b128 v[188:191], v2
	ds_read_b128 v[192:195], v2 offset:512
	s_lshl_b32 s7, s7, 13
	v_add_u32_e32 v2, s7, v137
	ds_read_b128 v[196:199], v2
	ds_read_b128 v[200:203], v2 offset:512
	ds_read_b128 v[204:207], v2 offset:2048
	ds_read_b128 v[208:211], v2 offset:2560
	ds_read_b128 v[212:215], v2 offset:4096
	ds_read_b128 v[216:219], v2 offset:4608
	ds_read_b128 v[220:223], v2 offset:6144
	ds_read_b128 v[224:227], v2 offset:6656
	s_addk_i32 s12, 0x1fff
	s_cmp_le_u32 s12, s70
	v_add_u32_e32 v186, s7, v165
	s_waitcnt lgkmcnt(9)
	v_mfma_f32_32x32x16_bf16 v[82:97], v[188:191], v[114:117], v[50:65]
	s_waitcnt lgkmcnt(8)
	v_mfma_f32_32x32x16_bf16 v[98:113], v[192:195], v[114:117], v[50:65]
	s_waitcnt lgkmcnt(7)
	v_mfma_f32_32x32x16_bf16 v[82:97], v[196:199], v[118:121], v[82:97]
	s_waitcnt lgkmcnt(6)
	v_mfma_f32_32x32x16_bf16 v[98:113], v[200:203], v[118:121], v[98:113]
	s_waitcnt lgkmcnt(5)
	v_mfma_f32_32x32x16_bf16 v[82:97], v[204:207], v[122:125], v[82:97]
	s_waitcnt lgkmcnt(4)
	v_mfma_f32_32x32x16_bf16 v[98:113], v[208:211], v[122:125], v[98:113]
	s_waitcnt lgkmcnt(3)
	v_mfma_f32_32x32x16_bf16 v[82:97], v[212:215], v[126:129], v[82:97]
	s_waitcnt lgkmcnt(2)
	v_mfma_f32_32x32x16_bf16 v[98:113], v[216:219], v[126:129], v[98:113]
	s_waitcnt lgkmcnt(1)
	v_mfma_f32_32x32x16_bf16 v[82:97], v[220:223], v[130:133], v[82:97]
	s_waitcnt lgkmcnt(0)
	v_mfma_f32_32x32x16_bf16 v[98:113], v[224:227], v[130:133], v[98:113]
	ds_read_b64_tr_b16 v[188:189], v186 offset:32768
	ds_read_b64_tr_b16 v[190:191], v186 offset:33280
	ds_read_b64_tr_b16 v[192:193], v186 offset:36864
	ds_read_b64_tr_b16 v[194:195], v186 offset:37376
	ds_read_b64_tr_b16 v[196:197], v186 offset:33792
	ds_read_b64_tr_b16 v[198:199], v186 offset:34304
	ds_read_b64_tr_b16 v[200:201], v186 offset:37888
	ds_read_b64_tr_b16 v[202:203], v186 offset:38400
	ds_read_b64_tr_b16 v[204:205], v186 offset:34816
	ds_read_b64_tr_b16 v[206:207], v186 offset:35328
	ds_read_b64_tr_b16 v[208:209], v186 offset:38912
	ds_read_b64_tr_b16 v[210:211], v186 offset:39424
	ds_read_b64_tr_b16 v[212:213], v186 offset:35840
	ds_read_b64_tr_b16 v[214:215], v186 offset:36352
	ds_read_b64_tr_b16 v[216:217], v186 offset:39936
	ds_read_b64_tr_b16 v[218:219], v186 offset:40448
	s_cbranch_scc1 .LBB0_430
	v_add_u32_e32 v2, s71, v155
	v_add_u32_e32 v2, 0xc0, v2
	s_movk_i32 s40, 0xffe6
	s_movk_i32 s68, 0xffe5
	s_movk_i32 s38, 0xffe7
	v_cmp_lt_i32_e64 s[66:67], s40, v2
	v_cmp_lt_i32_e64 s[68:69], s68, v2
	s_movk_i32 s36, 0xffe8
	v_cmp_lt_i32_e64 s[64:65], s38, v2
	s_and_b64 s[66:67], s[68:69], s[66:67]
	s_movk_i32 s34, 0xffed
	v_cmp_lt_i32_e64 s[62:63], s36, v2
	s_and_b64 s[64:65], s[66:67], s[64:65]
	s_movk_i32 s30, 0xffee
	v_cmp_lt_i32_e64 s[60:61], s34, v2
	s_and_b64 s[62:63], s[64:65], s[62:63]
	s_movk_i32 s28, 0xffef
	v_cmp_lt_i32_e64 s[58:59], s30, v2
	s_and_b64 s[60:61], s[62:63], s[60:61]
	v_cmp_lt_i32_e64 s[56:57], s28, v2
	s_and_b64 s[58:59], s[60:61], s[58:59]
	v_cmp_lt_i32_e64 s[54:55], -16, v2
	s_and_b64 s[56:57], s[58:59], s[56:57]
	v_cmp_lt_i32_e64 s[52:53], -11, v2
	s_and_b64 s[54:55], s[56:57], s[54:55]
	v_cmp_lt_i32_e64 s[50:51], -10, v2
	s_and_b64 s[52:53], s[54:55], s[52:53]
	v_cmp_lt_i32_e64 s[48:49], -9, v2
	s_and_b64 s[50:51], s[52:53], s[50:51]
	s_movk_i32 s14, 0xffe0
	v_cmp_lt_i32_e64 s[46:47], -8, v2
	s_and_b64 s[48:49], s[50:51], s[48:49]
	v_cmp_gt_i32_e64 s[12:13], 1, v2
	v_cmp_lt_i32_e32 vcc, s14, v2
	v_cmp_gt_i32_e64 s[14:15], 0, v2
	v_cmp_lt_i32_e64 s[44:45], -3, v2
	s_and_b64 s[46:47], s[48:49], s[46:47]
	s_or_b64 s[12:13], s[14:15], s[12:13]
	v_cmp_lt_i32_e64 s[42:43], -2, v2
	s_and_b64 s[44:45], s[46:47], s[44:45]
	v_cndmask_b32_e64 v4, v174, v83, s[14:15]
	v_cndmask_b32_e64 v5, v174, v82, s[12:13]
	s_and_b64 s[42:43], s[44:45], s[42:43]
	s_movk_i32 s40, 0xffc6
	v_cndmask_b32_e64 v82, v82, v5, s[42:43]
	v_cndmask_b32_e64 v84, v84, v174, s[42:43]
	v_cndmask_b32_e64 v83, v83, v4, s[42:43]
	s_movk_i32 s42, 0xffc5
	s_movk_i32 s38, 0xffc7
	v_cmp_lt_i32_e64 s[40:41], s40, v2
	v_cmp_lt_i32_e64 s[42:43], s42, v2
	s_movk_i32 s36, 0xffc8
	v_cmp_lt_i32_e64 s[38:39], s38, v2
	s_and_b64 s[40:41], s[42:43], s[40:41]
	s_movk_i32 s34, 0xffcd
	v_cmp_lt_i32_e64 s[36:37], s36, v2
	s_and_b64 s[38:39], s[40:41], s[38:39]
	s_movk_i32 s30, 0xffce
	v_cmp_lt_i32_e64 s[34:35], s34, v2
	s_and_b64 s[36:37], s[38:39], s[36:37]
	s_movk_i32 s28, 0xffcf
	v_cmp_lt_i32_e64 s[30:31], s30, v2
	s_and_b64 s[34:35], s[36:37], s[34:35]
	s_movk_i32 s26, 0xffd0
	v_cmp_lt_i32_e64 s[28:29], s28, v2
	s_and_b64 s[30:31], s[34:35], s[30:31]
	s_movk_i32 s24, 0xffd5
	v_cmp_lt_i32_e64 s[26:27], s26, v2
	s_and_b64 s[28:29], s[30:31], s[28:29]
	s_movk_i32 s22, 0xffd6
	v_cmp_lt_i32_e64 s[24:25], s24, v2
	s_and_b64 s[26:27], s[28:29], s[26:27]
	s_movk_i32 s20, 0xffd7
	v_cmp_lt_i32_e64 s[22:23], s22, v2
	s_and_b64 s[24:25], s[26:27], s[24:25]
	s_movk_i32 s18, 0xffd8
	v_cmp_lt_i32_e64 s[20:21], s20, v2
	s_and_b64 s[22:23], s[24:25], s[22:23]
	s_movk_i32 s16, 0xffdd
	v_cmp_lt_i32_e64 s[18:19], s18, v2
	s_and_b64 s[20:21], s[22:23], s[20:21]
	s_movk_i32 s14, 0xffde
	v_cmp_lt_i32_e64 s[16:17], s16, v2
	s_and_b64 s[18:19], s[20:21], s[18:19]
	s_movk_i32 s12, 0xffdf
	v_cmp_lt_i32_e64 s[14:15], s14, v2
	s_and_b64 s[16:17], s[18:19], s[16:17]
	v_cmp_lt_i32_e64 s[12:13], s12, v2
; #define LAS3 __attribute__((address_space(3)))
; __device__ __forceinline__ unsigned cvtpk(float lo, float hi) { f32x2_t v = {lo, hi}; bf16x2_t b = __builtin_convertvector(v, bf16x2_t); return __builtin_bit_cast(unsigned, b); }
; __device__ __forceinline__ s16x4 vtr(const LAS3 unsigned char* p) { return __builtin_bit_cast(s16x4, __builtin_amdgcn_ds_read_tr16_b64_v4i16((LAS3 v4i16_t*)p)); }
; __device__ __forceinline__ void fox_unit(int b, int hh, int qb, const bf16_t* Q, const bf16_t* __restrict__ K, const bf16_t* __restrict__ V, bf16_t* O, ...
;     ...
;             if (64 * jt + 63 > qw0) { const int kb_ = 64 * jt + 4 * hi - (qw0 + r32);
; #pragma unroll
;                 for (int r = 0; r < 16; ++r) { const int cr = (r & 3) + 8 * (r >> 2); if (kb_ + cr > 0) p0[r] = -INFINITY; if (kb_ + cr + 32 > 0) p1[r] = -INFINITY; } }
; #pragma unroll
;             for (int r = 0; r < 16; ++r) { p0[r] = __builtin_amdgcn_exp2f(p0[r]); p1[r] = __builtin_amdgcn_exp2f(p1[r]); }
;             u32x4 pw[4];
; #pragma unroll
;             for (int i = 0; i < 4; ++i) { pw[0][i] = cvtpk(p0[2 * i], p0[2 * i + 1]); pw[1][i] = cvtpk(p0[8 + 2 * i], p0[8 + 2 * i + 1]); pw[2][i] = cvtpk(p1[2 * i], p1[2 * i + 1]); pw[3][i] = cvtpk(p1[8 + 2 * i], p1[8 + 2 * i + 1]); }
;             const LAS3 unsigned char* vp = vp0 + slot * SLOTB;
; #pragma unroll
;             for (int ks = 0; ks < 4; ++ks) {
;                 const s16x4 l0 = vtr(vp + ks * 1024), h0 = vtr(vp + ks * 1024 + 512), l1 = vtr(vp + 4096 + ks * 1024), h1 = vtr(vp + 4096 + ks * 1024 + 512);
;                 const bf16x8 v0 = (bf16x8){l0[0], l0[1], l0[2], l0[3], h0[0], h0[1], h0[2], h0[3]}, v1 = (bf16x8){l1[0], l1[1], l1[2], l1[3], h1[0], h1[1], h1[2], h1[3]};
;                 const bf16x8 pf = __builtin_bit_cast(bf16x8, pw[ks]);
;                 o0 = __builtin_amdgcn_mfma_f32_32x32x16_bf16(v0, pf, o0, 0, 0, 0);
;                 o1 = __builtin_amdgcn_mfma_f32_32x32x16_bf16(v1, pf, o1, 0, 0, 0);
;                 lacc = __builtin_amdgcn_mfma_f32_32x32x16_bf16(onesA, pf, lacc, 0, 0, 0);
;             }
	s_and_b64 s[14:15], s[16:17], s[14:15]
	s_and_b64 s[12:13], s[14:15], s[12:13]
	s_and_b64 vcc, s[12:13], vcc
	v_cndmask_b32_e64 v97, v97, v174, s[68:69]
	v_cndmask_b32_e64 v96, v96, v174, s[66:67]
	v_cndmask_b32_e64 v95, v95, v174, s[64:65]
	v_cndmask_b32_e64 v94, v94, v174, s[62:63]
	v_cndmask_b32_e64 v93, v93, v174, s[60:61]
	v_cndmask_b32_e64 v92, v92, v174, s[58:59]
	v_cndmask_b32_e64 v91, v91, v174, s[56:57]
	v_cndmask_b32_e64 v90, v90, v174, s[54:55]
	v_cndmask_b32_e64 v89, v89, v174, s[52:53]
	v_cndmask_b32_e64 v88, v88, v174, s[50:51]
	v_cndmask_b32_e64 v87, v87, v174, s[48:49]
	v_cndmask_b32_e64 v86, v86, v174, s[46:47]
	v_cndmask_b32_e64 v85, v85, v174, s[44:45]
	v_cndmask_b32_e64 v113, v113, v174, s[42:43]
	v_cndmask_b32_e64 v112, v112, v174, s[40:41]
	v_cndmask_b32_e64 v111, v111, v174, s[38:39]
	v_cndmask_b32_e64 v110, v110, v174, s[36:37]
	v_cndmask_b32_e64 v109, v109, v174, s[34:35]
	v_cndmask_b32_e64 v108, v108, v174, s[30:31]
	v_cndmask_b32_e64 v107, v107, v174, s[28:29]
	v_cndmask_b32_e64 v106, v106, v174, s[26:27]
	v_cndmask_b32_e64 v105, v105, v174, s[24:25]
	v_cndmask_b32_e64 v104, v104, v174, s[22:23]
	v_cndmask_b32_e64 v103, v103, v174, s[20:21]
	v_cndmask_b32_e64 v102, v102, v174, s[18:19]
	v_cndmask_b32_e64 v101, v101, v174, s[16:17]
	v_cndmask_b32_e64 v100, v100, v174, s[14:15]
	v_cndmask_b32_e64 v99, v99, v174, s[12:13]
	v_cndmask_b32_e32 v98, v98, v174, vcc
.LBB0_430:
	s_nop 7
	v_exp_f32_e32 v2, v82
	v_exp_f32_e32 v5, v83
	s_nop 0
	v_exp_f32_e32 v4, v98
	v_exp_f32_e32 v6, v99
	v_exp_f32_e32 v7, v84
	v_exp_f32_e32 v10, v85
	v_exp_f32_e32 v12, v86
	v_exp_f32_e32 v13, v102
	v_exp_f32_e32 v14, v87
	v_exp_f32_e32 v15, v103
	v_exp_f32_e32 v16, v88
	v_exp_f32_e32 v85, v89
	v_exp_f32_e32 v8, v90
	v_exp_f32_e32 v83, v106
	v_exp_f32_e32 v82, v91
	v_exp_f32_e32 v84, v107
	v_exp_f32_e32 v88, v92
	v_exp_f32_e32 v89, v108
	v_exp_f32_e32 v90, v93
	v_exp_f32_e32 v91, v109
	v_exp_f32_e32 v92, v94
	v_exp_f32_e32 v93, v110
	v_exp_f32_e32 v94, v95
	v_exp_f32_e32 v95, v111
	v_cvt_pk_bf16_f32 v86, v2, v5
	v_cvt_pk_bf16_f32 v82, v8, v82
	v_cvt_pk_bf16_f32 v8, v4, v6
	v_cvt_pk_bf16_f32 v4, v83, v84
	v_cvt_pk_bf16_f32 v87, v7, v10
	v_cvt_pk_bf16_f32 v83, v88, v90
	v_cvt_pk_bf16_f32 v5, v89, v91
	v_cvt_pk_bf16_f32 v88, v12, v14
	v_cvt_pk_bf16_f32 v84, v92, v94
	v_cvt_pk_bf16_f32 v10, v13, v15
	v_cvt_pk_bf16_f32 v6, v93, v95
	v_cvt_pk_bf16_f32 v89, v16, v85
	s_mov_b32 s77, s76
	s_mov_b32 s78, s76
	s_waitcnt lgkmcnt(0)
	v_mfma_f32_32x32x16_bf16 v[34:49], v[188:191], v[86:89], v[34:49]
	s_mov_b32 s79, s76
	v_mov_b64_e32 v[12:13], s[76:77]
	v_mov_b64_e32 v[14:15], s[78:79]
	v_exp_f32_e32 v96, v96
	v_exp_f32_e32 v97, v97
	v_exp_f32_e32 v9, v100
	v_exp_f32_e32 v11, v101
	v_mfma_f32_32x32x16_bf16 v[18:33], v[192:195], v[86:89], v[18:33]
	v_cvt_pk_bf16_f32 v85, v96, v97
	v_exp_f32_e32 v17, v104
	v_exp_f32_e32 v98, v105
	v_cvt_pk_bf16_f32 v9, v9, v11
	v_exp_f32_e32 v99, v112
	v_exp_f32_e32 v100, v113
	v_cvt_pk_bf16_f32 v11, v17, v98
	v_mfma_f32_32x32x16_bf16 v[66:81], v[12:15], v[86:89], v[66:81]
	v_cvt_pk_bf16_f32 v7, v99, v100
	v_mfma_f32_32x32x16_bf16 v[34:49], v[196:199], v[82:85], v[34:49]
	v_mfma_f32_32x32x16_bf16 v[18:33], v[200:203], v[82:85], v[18:33]
	v_mfma_f32_32x32x16_bf16 v[66:81], v[12:15], v[82:85], v[66:81]
	v_mfma_f32_32x32x16_bf16 v[34:49], v[204:207], v[8:11], v[34:49]
	v_mfma_f32_32x32x16_bf16 v[18:33], v[208:211], v[8:11], v[18:33]
	v_mfma_f32_32x32x16_bf16 v[66:81], v[12:15], v[8:11], v[66:81]
	v_mfma_f32_32x32x16_bf16 v[34:49], v[212:215], v[4:7], v[34:49]
	v_mfma_f32_32x32x16_bf16 v[18:33], v[216:219], v[4:7], v[18:33]
	v_mfma_f32_32x32x16_bf16 v[66:81], v[12:15], v[4:7], v[66:81]
; #define LAS3 __attribute__((address_space(3)))
; __device__ __forceinline__ unsigned cvtpk(float lo, float hi) { f32x2_t v = {lo, hi}; bf16x2_t b = __builtin_convertvector(v, bf16x2_t); return __builtin_bit_cast(unsigned, b); }
; __device__ __forceinline__ s16x4 vtr(const LAS3 unsigned char* p) { return __builtin_bit_cast(s16x4, __builtin_amdgcn_ds_read_tr16_b64_v4i16((LAS3 v4i16_t*)p)); }
; __device__ __forceinline__ void fox_unit(int b, int hh, int qb, const bf16_t* Q, const bf16_t* __restrict__ K, const bf16_t* __restrict__ V, bf16_t* O, ...
;     ...
;             const LAS3 unsigned char* kp = kp0 + slot * SLOTB; const LAS3 unsigned char* fp = fp0 + slot * 1024;
;             asm volatile("" : "+v"(cinit));
;             f32x16 p0 = __builtin_amdgcn_mfma_f32_32x32x16_bf16(*(const LAS3 bf16x8*)(fp), qones, cinit, 0, 0, 0);
;             f32x16 p1 = __builtin_amdgcn_mfma_f32_32x32x16_bf16(*(const LAS3 bf16x8*)(fp + 512), qones, cinit, 0, 0, 0);
; #pragma unroll
;             for (int d0 = 0; d0 < 4; ++d0) {
;                 const bf16x8 k0 = *(const LAS3 bf16x8*)(kp + d0 * 2048), k1 = *(const LAS3 bf16x8*)(kp + d0 * 2048 + 512);
;                 p0 = __builtin_amdgcn_mfma_f32_32x32x16_bf16(k0, qr[d0], p0, 0, 0, 0);
;                 p1 = __builtin_amdgcn_mfma_f32_32x32x16_bf16(k1, qr[d0], p1, 0, 0, 0);
;             }
;             if (64 * jt + 63 > qw0) { const int kb_ = 64 * jt + 4 * hi - (qw0 + r32);
; #pragma unroll
;                 for (int r = 0; r < 16; ++r) { const int cr = (r & 3) + 8 * (r >> 2); if (kb_ + cr > 0) p0[r] = -INFINITY; if (kb_ + cr + 32 > 0) p1[r] = -INFINITY; } }
; #pragma unroll
;             for (int r = 0; r < 16; ++r) { p0[r] = __builtin_amdgcn_exp2f(p0[r]); p1[r] = __builtin_amdgcn_exp2f(p1[r]); }
;             u32x4 pw[4];
; #pragma unroll
;             for (int i = 0; i < 4; ++i) { pw[0][i] = cvtpk(p0[2 * i], p0[2 * i + 1]); pw[1][i] = cvtpk(p0[8 + 2 * i], p0[8 + 2 * i + 1]); pw[2][i] = cvtpk(p1[2 * i], p1[2 * i + 1]); pw[3][i] = cvtpk(p1[8 + 2 * i], p1[8 + 2 * i + 1]); }
;             const LAS3 unsigned char* vp = vp0 + slot * SLOTB;
; #pragma unroll
;             for (int ks = 0; ks < 4; ++ks) {
;                 const s16x4 l0 = vtr(vp + ks * 1024), h0 = vtr(vp + ks * 1024 + 512), l1 = vtr(vp + 4096 + ks * 1024), h1 = vtr(vp + 4096 + ks * 1024 + 512);
.LBB0_431:
	s_add_i32 s12, s2, s71
	s_add_i32 s7, s12, 0xffffff80
	s_cmp_le_u32 s7, s33
	s_cselect_b64 s[14:15], -1, 0
	s_and_b64 s[14:15], s[14:15], s[94:95]
	s_andn2_b64 vcc, exec, s[14:15]
	s_cbranch_vccnz .LBB0_435
	s_add_i32 s7, s6, 2
	s_and_b32 s7, s7, 2
	v_lshl_add_u32 v2, s7, 10, v166
	ds_read_b128 v[188:191], v2
	ds_read_b128 v[192:195], v2 offset:512
	s_lshl_b32 s7, s7, 13
	v_add_u32_e32 v2, s7, v137
	ds_read_b128 v[196:199], v2
	ds_read_b128 v[200:203], v2 offset:512
	ds_read_b128 v[204:207], v2 offset:2048
	ds_read_b128 v[208:211], v2 offset:2560
	ds_read_b128 v[212:215], v2 offset:4096
	ds_read_b128 v[216:219], v2 offset:4608
	ds_read_b128 v[220:223], v2 offset:6144
	ds_read_b128 v[224:227], v2 offset:6656
	s_addk_i32 s12, 0xffbf
	s_cmp_le_u32 s12, s70
	v_add_u32_e32 v186, s7, v165
	s_waitcnt lgkmcnt(9)
	v_mfma_f32_32x32x16_bf16 v[82:97], v[188:191], v[114:117], v[50:65]
	s_waitcnt lgkmcnt(8)
	v_mfma_f32_32x32x16_bf16 v[98:113], v[192:195], v[114:117], v[50:65]
	s_waitcnt lgkmcnt(7)
	v_mfma_f32_32x32x16_bf16 v[82:97], v[196:199], v[118:121], v[82:97]
	s_waitcnt lgkmcnt(6)
	v_mfma_f32_32x32x16_bf16 v[98:113], v[200:203], v[118:121], v[98:113]
	s_waitcnt lgkmcnt(5)
	v_mfma_f32_32x32x16_bf16 v[82:97], v[204:207], v[122:125], v[82:97]
	s_waitcnt lgkmcnt(4)
	v_mfma_f32_32x32x16_bf16 v[98:113], v[208:211], v[122:125], v[98:113]
	s_waitcnt lgkmcnt(3)
	v_mfma_f32_32x32x16_bf16 v[82:97], v[212:215], v[126:129], v[82:97]
	s_waitcnt lgkmcnt(2)
	v_mfma_f32_32x32x16_bf16 v[98:113], v[216:219], v[126:129], v[98:113]
	s_waitcnt lgkmcnt(1)
	v_mfma_f32_32x32x16_bf16 v[82:97], v[220:223], v[130:133], v[82:97]
	s_waitcnt lgkmcnt(0)
	v_mfma_f32_32x32x16_bf16 v[98:113], v[224:227], v[130:133], v[98:113]
	ds_read_b64_tr_b16 v[188:189], v186 offset:32768
	ds_read_b64_tr_b16 v[190:191], v186 offset:33280
	ds_read_b64_tr_b16 v[192:193], v186 offset:36864
	ds_read_b64_tr_b16 v[194:195], v186 offset:37376
	ds_read_b64_tr_b16 v[196:197], v186 offset:33792
	ds_read_b64_tr_b16 v[198:199], v186 offset:34304
	ds_read_b64_tr_b16 v[200:201], v186 offset:37888
	ds_read_b64_tr_b16 v[202:203], v186 offset:38400
	ds_read_b64_tr_b16 v[204:205], v186 offset:34816
	ds_read_b64_tr_b16 v[206:207], v186 offset:35328
	ds_read_b64_tr_b16 v[208:209], v186 offset:38912
	ds_read_b64_tr_b16 v[210:211], v186 offset:39424
	ds_read_b64_tr_b16 v[212:213], v186 offset:35840
	ds_read_b64_tr_b16 v[214:215], v186 offset:36352
	ds_read_b64_tr_b16 v[216:217], v186 offset:39936
	ds_read_b64_tr_b16 v[218:219], v186 offset:40448
	s_cbranch_scc1 .LBB0_434
	v_add_u32_e32 v2, s71, v153
	s_movk_i32 s40, 0xffe6
	s_movk_i32 s68, 0xffe5
	s_movk_i32 s38, 0xffe7
	v_cmp_lt_i32_e64 s[66:67], s40, v2
	v_cmp_lt_i32_e64 s[68:69], s68, v2
	s_movk_i32 s36, 0xffe8
	v_cmp_lt_i32_e64 s[64:65], s38, v2
	s_and_b64 s[66:67], s[68:69], s[66:67]
	s_movk_i32 s34, 0xffed
	v_cmp_lt_i32_e64 s[62:63], s36, v2
	s_and_b64 s[64:65], s[66:67], s[64:65]
	s_movk_i32 s30, 0xffee
	v_cmp_lt_i32_e64 s[60:61], s34, v2
	s_and_b64 s[62:63], s[64:65], s[62:63]
	s_movk_i32 s28, 0xffef
	v_cmp_lt_i32_e64 s[58:59], s30, v2
	s_and_b64 s[60:61], s[62:63], s[60:61]
	v_cmp_lt_i32_e64 s[56:57], s28, v2
	s_and_b64 s[58:59], s[60:61], s[58:59]
	v_cmp_lt_i32_e64 s[54:55], -16, v2
	s_and_b64 s[56:57], s[58:59], s[56:57]
	v_cmp_lt_i32_e64 s[52:53], -11, v2
	s_and_b64 s[54:55], s[56:57], s[54:55]
	v_cmp_lt_i32_e64 s[50:51], -10, v2
	s_and_b64 s[52:53], s[54:55], s[52:53]
	v_cmp_lt_i32_e64 s[48:49], -9, v2
	s_and_b64 s[50:51], s[52:53], s[50:51]
	s_movk_i32 s14, 0xffe0
	v_cmp_lt_i32_e64 s[46:47], -8, v2
	s_and_b64 s[48:49], s[50:51], s[48:49]
	v_cmp_gt_i32_e64 s[12:13], 1, v2
	v_cmp_lt_i32_e32 vcc, s14, v2
	v_cmp_gt_i32_e64 s[14:15], 0, v2
	v_cmp_lt_i32_e64 s[44:45], -3, v2
	s_and_b64 s[46:47], s[48:49], s[46:47]
	s_or_b64 s[12:13], s[14:15], s[12:13]
	v_cmp_lt_i32_e64 s[42:43], -2, v2
	s_and_b64 s[44:45], s[46:47], s[44:45]
	v_cndmask_b32_e64 v4, v174, v83, s[14:15]
	v_cndmask_b32_e64 v5, v174, v82, s[12:13]
	s_and_b64 s[42:43], s[44:45], s[42:43]
	s_movk_i32 s40, 0xffc6
	v_cndmask_b32_e64 v82, v82, v5, s[42:43]
	v_cndmask_b32_e64 v84, v84, v174, s[42:43]
	v_cndmask_b32_e64 v83, v83, v4, s[42:43]
	s_movk_i32 s42, 0xffc5
	s_movk_i32 s38, 0xffc7
	v_cmp_lt_i32_e64 s[40:41], s40, v2
	v_cmp_lt_i32_e64 s[42:43], s42, v2
	s_movk_i32 s36, 0xffc8
	v_cmp_lt_i32_e64 s[38:39], s38, v2
	s_and_b64 s[40:41], s[42:43], s[40:41]
	s_movk_i32 s34, 0xffcd
	v_cmp_lt_i32_e64 s[36:37], s36, v2
	s_and_b64 s[38:39], s[40:41], s[38:39]
	s_movk_i32 s30, 0xffce
	v_cmp_lt_i32_e64 s[34:35], s34, v2
	s_and_b64 s[36:37], s[38:39], s[36:37]
	s_movk_i32 s28, 0xffcf
	v_cmp_lt_i32_e64 s[30:31], s30, v2
	s_and_b64 s[34:35], s[36:37], s[34:35]
	s_movk_i32 s26, 0xffd0
	v_cmp_lt_i32_e64 s[28:29], s28, v2
	s_and_b64 s[30:31], s[34:35], s[30:31]
	s_movk_i32 s24, 0xffd5
	v_cmp_lt_i32_e64 s[26:27], s26, v2
	s_and_b64 s[28:29], s[30:31], s[28:29]
	s_movk_i32 s22, 0xffd6
	v_cmp_lt_i32_e64 s[24:25], s24, v2
	s_and_b64 s[26:27], s[28:29], s[26:27]
	s_movk_i32 s20, 0xffd7
	v_cmp_lt_i32_e64 s[22:23], s22, v2
	s_and_b64 s[24:25], s[26:27], s[24:25]
	s_movk_i32 s18, 0xffd8
	v_cmp_lt_i32_e64 s[20:21], s20, v2
	s_and_b64 s[22:23], s[24:25], s[22:23]
	s_movk_i32 s16, 0xffdd
	v_cmp_lt_i32_e64 s[18:19], s18, v2
	s_and_b64 s[20:21], s[22:23], s[20:21]
	s_movk_i32 s14, 0xffde
	v_cmp_lt_i32_e64 s[16:17], s16, v2
	s_and_b64 s[18:19], s[20:21], s[18:19]
	s_movk_i32 s12, 0xffdf
	v_cmp_lt_i32_e64 s[14:15], s14, v2
	s_and_b64 s[16:17], s[18:19], s[16:17]
	v_cmp_lt_i32_e64 s[12:13], s12, v2
	s_and_b64 s[14:15], s[16:17], s[14:15]
	s_and_b64 s[12:13], s[14:15], s[12:13]
	s_and_b64 vcc, s[12:13], vcc
	v_cndmask_b32_e64 v97, v97, v174, s[68:69]
	v_cndmask_b32_e64 v96, v96, v174, s[66:67]
	v_cndmask_b32_e64 v95, v95, v174, s[64:65]
	v_cndmask_b32_e64 v94, v94, v174, s[62:63]
	v_cndmask_b32_e64 v93, v93, v174, s[60:61]
	v_cndmask_b32_e64 v92, v92, v174, s[58:59]
	v_cndmask_b32_e64 v91, v91, v174, s[56:57]
	v_cndmask_b32_e64 v90, v90, v174, s[54:55]
	v_cndmask_b32_e64 v89, v89, v174, s[52:53]
	v_cndmask_b32_e64 v88, v88, v174, s[50:51]
	v_cndmask_b32_e64 v87, v87, v174, s[48:49]
	v_cndmask_b32_e64 v86, v86, v174, s[46:47]
	v_cndmask_b32_e64 v85, v85, v174, s[44:45]
	v_cndmask_b32_e64 v113, v113, v174, s[42:43]
	v_cndmask_b32_e64 v112, v112, v174, s[40:41]
	v_cndmask_b32_e64 v111, v111, v174, s[38:39]
	v_cndmask_b32_e64 v110, v110, v174, s[36:37]
	v_cndmask_b32_e64 v109, v109, v174, s[34:35]
	v_cndmask_b32_e64 v108, v108, v174, s[30:31]
	v_cndmask_b32_e64 v107, v107, v174, s[28:29]
	v_cndmask_b32_e64 v106, v106, v174, s[26:27]
	v_cndmask_b32_e64 v105, v105, v174, s[24:25]
	v_cndmask_b32_e64 v104, v104, v174, s[22:23]
	v_cndmask_b32_e64 v103, v103, v174, s[20:21]
	v_cndmask_b32_e64 v102, v102, v174, s[18:19]
	v_cndmask_b32_e64 v101, v101, v174, s[16:17]
	v_cndmask_b32_e64 v100, v100, v174, s[14:15]
	v_cndmask_b32_e64 v99, v99, v174, s[12:13]
	v_cndmask_b32_e32 v98, v98, v174, vcc
